# v63 + FF1: weight rows remapped so each wave owns 64 contiguous output columns (bf16 U stores of a wave fill whole 128B lines); half-step K<<6, epilogue column base wc*64, second store offset 64
# speedup vs baseline: 1.0029x; 1.0029x over previous
.LBB0_197:
	v_readlane_b32 s2, v237, 15
	s_waitcnt vmcnt(0)
	v_mov_b32_e32 v18, v190
	v_readlane_b32 s3, v237, 16
	s_movk_i32 s42, 0x400
	v_readfirstlane_b32 s31, v18
	s_movk_i32 s38, 0x400
	s_andn2_b64 vcc, exec, s[2:3]
	s_cbranch_vccnz .LBB0_219
	v_lshlrev_b32_e32 v0, 4, v18
	v_add_u32_e32 v2, 0x2000, v0
	s_waitcnt lgkmcnt(0)
	v_ashrrev_i32_e32 v3, 31, v2
	v_lshrrev_b32_e32 v3, 22, v3
	v_add_u32_e32 v3, v2, v3
	v_ashrrev_i32_e32 v3, 10, v3
	v_mul_i32_i24_e32 v4, 0x400, v3
	v_sub_u32_e32 v2, v2, v4
	v_lshrrev_b32_e32 v4, 4, v2
	v_bitop3_b32 v2, v4, v2, 32 bitop3:0x6c
	v_ashrrev_i32_e32 v4, 31, v2
	v_lshrrev_b32_e32 v4, 26, v4
	v_add_u32_e32 v4, v2, v4
	v_lshlrev_b32_e32 v6, 3, v3
	v_ashrrev_i32_e32 v5, 6, v4
	v_and_b32_e32 v6, -16, v6
	v_lshlrev_b32_e32 v3, 5, v3
	s_lshl_b32 s4, s97, 3
	v_readlane_b32 s27, v236, 12
	v_add_u32_e32 v6, v5, v6
	v_and_b32_e32 v20, 32, v3
	v_and_b32_e32 v3, 0xc0, v4
	s_or_b32 s54, s4, s27
	v_and_b32_e32 v5, 3, v5
	s_mov_b32 s27, 0x7fffffe0
	v_lshrrev_b32_e32 v7, 2, v6
	v_lshlrev_b32_e32 v8, 1, v6
	v_sub_u32_e32 v2, v2, v3
	v_and_or_b32 v5, v6, s27, v5
	v_and_b32_e32 v7, 4, v7
	v_and_b32_e32 v8, 24, v8
	v_ashrrev_i16_sdwa v2, v193, sext(v2) dst_sel:DWORD dst_unused:UNUSED_PAD src0_sel:DWORD src1_sel:BYTE_0
	v_or3_b32 v5, v5, v7, v8
	v_bfe_i32 v21, v2, 0, 16
	v_and_b32_e32 v7, -32, v6
	v_add_u32_e32 v5, v5, v7
	v_mul_lo_u32 v5, v5, s42
	v_add_u32_e32 v2, v20, v21
	v_mul_lo_u32 v22, v6, s38
	v_add_lshl_u32 v130, v5, v2, 1
	v_add_lshl_u32 v132, v2, v22, 1
	v_bfe_i32 v2, v18, 27, 1
	v_lshrrev_b32_e32 v2, 22, v2
	v_add_u32_e32 v2, v0, v2
	v_and_b32_e32 v2, 0xfffffc00, v2
	v_sub_u32_e32 v0, v0, v2
	v_lshrrev_b32_e32 v2, 4, v0
	v_ashrrev_i32_e32 v19, 31, v18
	v_bitop3_b32 v2, v2, v0, 32 bitop3:0x6c
	v_lshrrev_b32_e32 v4, 26, v19
	v_ashrrev_i32_e32 v0, 31, v2
	v_add_u32_e32 v4, v18, v4
	v_lshrrev_b32_e32 v0, 26, v0
	v_ashrrev_i32_e32 v4, 6, v4
	v_add_u32_e32 v3, v2, v0
	v_lshlrev_b32_e32 v5, 3, v4
	v_ashrrev_i32_e32 v0, 6, v3
	v_and_b32_e32 v5, -16, v5
	s_ashr_i32 s43, s42, 31
	v_add_u32_e32 v5, v0, v5
	v_readlane_b32 s40, v236, 24
	s_ashr_i32 s39, s38, 31
	s_lshl_b64 s[34:35], s[42:43], 9
	v_and_b32_e32 v0, 3, v0
	v_lshrrev_b32_e32 v6, 2, v5
	v_lshlrev_b32_e32 v7, 1, v5
	v_readlane_b32 s41, v236, 25
	s_lshl_b64 s[2:3], s[38:39], 8
	v_and_or_b32 v0, v5, s27, v0
	v_and_b32_e32 v6, 4, v6
	v_and_b32_e32 v7, 24, v7
	v_and_b32_e32 v3, 0xc0, v3
	v_mul_lo_u32 v24, v5, s38
	s_mul_i32 s27, s34, s41
	s_mul_hi_u32 s30, s34, s40
	s_lshr_b64 s[38:39], s[42:43], 23
	s_ashr_i32 s46, s31, 6
	v_or3_b32 v0, v0, v6, v7
	v_sub_u32_e32 v2, v2, v3
	s_ashr_i32 s55, s54, 31
	s_add_i32 s27, s30, s27
	s_mul_i32 s30, s38, s40
	s_lshl_b64 s[6:7], s[42:43], 6
	s_lshl_b32 s5, s46, 10
	v_and_b32_e32 v7, -32, v5
	v_add_u32_e32 v0, v0, v7
	v_mul_lo_u32 v6, v0, s42
	v_lshlrev_b32_e32 v0, 5, v4
	v_ashrrev_i16_sdwa v2, v193, sext(v2) dst_sel:DWORD dst_unused:UNUSED_PAD src0_sel:DWORD src1_sel:BYTE_0
	s_lshl_b64 s[28:29], s[54:55], 19
	s_add_i32 s27, s27, s30
	s_mul_i32 s30, s34, s40
	v_readlane_b32 s38, v235, 15
	v_and_b32_e32 v0, 32, v0
	v_bfe_i32 v23, v2, 0, 16
	s_add_u32 s58, s38, s30
	v_readlane_b32 s30, v235, 16
	v_add_u32_e32 v2, v0, v23
	s_addc_u32 s59, s30, s27
	s_add_i32 s27, s5, 0
	v_add_lshl_u32 v134, v6, v2, 1
	s_add_i32 m0, s27, 0x10000
	v_add_lshl_u32 v136, v2, v24, 1
	global_load_lds_dwordx4 v134, s[58:59]
	s_add_i32 m0, s27, 0x12000
	s_add_u32 s44, s58, s6
	global_load_lds_dwordx4 v130, s[58:59]
	s_addc_u32 s45, s59, s7
	s_add_i32 m0, s27, 0x14000
	v_mov_b32_e32 v2, 0
	global_load_lds_dwordx4 v134, s[44:45]
	s_add_i32 m0, s27, 0x16000
	s_add_u32 s56, s22, s28
	s_addc_u32 s57, s23, s29
	s_add_i32 s28, s27, 0x2000
	global_load_lds_dwordx4 v130, s[44:45]
	s_mov_b32 m0, s27
	s_add_u32 s38, s56, s2
	global_load_lds_dwordx4 v136, s[56:57]
	s_mov_b32 m0, s28
	s_addc_u32 s39, s57, s3
	s_add_i32 s29, s27, 0x4000
	global_load_lds_dwordx4 v132, s[56:57]
	s_mov_b32 m0, s29
	s_add_i32 s30, s27, 0x6000
	global_load_lds_dwordx4 v136, s[38:39]
	s_mov_b32 m0, s30
	s_cmpk_lt_u32 s31, 0x100
	global_load_lds_dwordx4 v132, s[38:39]
	s_cselect_b64 s[38:39], -1, 0
	s_cmpk_gt_u32 s31, 0xff
	v_mov_b32_e32 v3, 0
	v_mov_b32_e32 v4, 0
	v_mov_b32_e32 v5, 0
	v_mov_b32_e32 v6, 0
	v_mov_b32_e32 v7, 0
	v_mov_b32_e32 v8, 0
	v_mov_b32_e32 v9, 0
	v_mov_b32_e32 v10, 0
	v_mov_b32_e32 v11, 0
	v_mov_b32_e32 v12, 0
	v_mov_b32_e32 v13, 0
	v_mov_b32_e32 v14, 0
	v_mov_b32_e32 v15, 0
	v_mov_b32_e32 v16, 0
	v_mov_b32_e32 v17, 0
	s_cbranch_scc1 .LBB0_200
	s_lshl_b64 s[40:41], s[54:55], 14
	v_readlane_b32 s47, v236, 63
	s_add_u32 s40, s47, s40
	v_readlane_b32 s47, v235, 0
	s_addc_u32 s41, s47, s41
	v_lshlrev_b64 v[2:3], 6, v[18:19]
	v_lshl_add_u64 v[14:15], s[40:41], 0, v[2:3]
	global_load_dwordx4 v[2:5], v[14:15], off offset:48
	global_load_dwordx4 v[6:9], v[14:15], off offset:32
	global_load_dwordx4 v[10:13], v[14:15], off offset:16
	s_nop 0
	global_load_dwordx4 v[14:17], v[14:15], off

.LBB0_215:
	v_mov_b32_e32 v0, v144
	v_mov_b32_e32 v142, v145
	s_lshl_b32 s50, s50, 8
	s_add_i32 s50, s50, s62
	s_add_i32 s50, s50, s62
	s_ashr_i32 s55, s54, 31
	v_add_u32_e32 v148, s61, v0
	v_lshl_add_u32 v142, v142, 3, s50
	s_lshl_b64 s[50:51], s[54:55], 21
	v_readlane_b32 s54, v236, 59
	s_add_u32 s54, s54, s50
	v_readlane_b32 s50, v236, 56
	v_and_b32_e32 v149, 0xff, v148
	s_addc_u32 s55, s50, s51
	v_lshlrev_b32_e32 v0, 13, v149
	s_add_i32 s50, 0, 0x20400
	v_lshl_add_u64 v[150:151], s[54:55], 0, v[0:1]
	v_lshl_add_u32 v0, v149, 2, s50
	ds_read_b32 v0, v0
	v_ashrrev_i32_e32 v143, 31, v142
	v_lshlrev_b64 v[142:143], 1, v[142:143]
	v_lshl_add_u64 v[150:151], v[150:151], 0, v[142:143]
	s_movk_i32 s51, 0x80
	s_waitcnt lgkmcnt(0)
	v_pk_mul_f32 v[124:125], v[124:125], v[0:1] op_sel_hi:[1,0]
	v_pk_mul_f32 v[122:123], v[122:123], v[0:1] op_sel_hi:[1,0]
	v_pk_mul_f32 v[128:129], v[128:129], v[0:1] op_sel_hi:[1,0]
	v_pk_mul_f32 v[126:127], v[126:127], v[0:1] op_sel_hi:[1,0]
	v_max_f32_e32 v122, 0, v122
	v_max_f32_e32 v126, 0, v126
	v_max_f32_e32 v123, 0, v123
	v_max_f32_e32 v127, 0, v127
	v_max_f32_e32 v124, 0, v124
	v_max_f32_e32 v128, 0, v128
	v_max_f32_e32 v125, 0, v125
	v_max_f32_e32 v129, 0, v129
	v_pk_mul_f32 v[122:123], v[122:123], v[122:123]
	v_pk_mul_f32 v[126:127], v[126:127], v[126:127]
	v_pk_mul_f32 v[124:125], v[124:125], v[124:125]
	v_pk_mul_f32 v[128:129], v[128:129], v[128:129]
	v_pk_mul_f32 v[114:115], v[114:115], v[0:1] op_sel_hi:[1,0]
	v_cvt_pk_bf16_f32 v122, v122, v123
	v_cvt_pk_bf16_f32 v123, v124, v125
	v_cvt_pk_bf16_f32 v124, v126, v127
	v_cvt_pk_bf16_f32 v125, v128, v129
	v_pk_mul_f32 v[120:121], v[120:121], v[0:1] op_sel_hi:[1,0]
	v_pk_mul_f32 v[118:119], v[118:119], v[0:1] op_sel_hi:[1,0]
	v_pk_mul_f32 v[116:117], v[116:117], v[0:1] op_sel_hi:[1,0]
	v_max_f32_e32 v114, 0, v114
	v_max_f32_e32 v115, 0, v115
	global_store_dwordx4 v[150:151], v[122:125], off
	v_max_f32_e32 v118, 0, v118
	v_max_f32_e32 v119, 0, v119
	v_pk_mul_f32 v[122:123], v[114:115], v[114:115]
	v_max_f32_e32 v114, 0, v120
	v_max_f32_e32 v116, 0, v116
	v_max_f32_e32 v115, 0, v121
	v_max_f32_e32 v117, 0, v117
	v_pk_mul_f32 v[118:119], v[118:119], v[118:119]
	v_pk_mul_f32 v[120:121], v[114:115], v[114:115]
	v_pk_mul_f32 v[124:125], v[116:117], v[116:117]
	v_cvt_pk_bf16_f32 v114, v118, v119
	v_cvt_pk_bf16_f32 v115, v120, v121
	v_cvt_pk_bf16_f32 v116, v122, v123
	v_cvt_pk_bf16_f32 v117, v124, v125
	v_add_u32_e32 v0, 16, v148
	global_store_dwordx4 v[150:151], v[114:117], off offset:64
	s_andn2_b64 vcc, exec, s[48:49]
	s_nop 0
	v_and_b32_e32 v116, 0xff, v0
	v_lshlrev_b32_e32 v0, 13, v116
	v_lshl_add_u64 v[114:115], s[54:55], 0, v[0:1]
	v_lshl_add_u32 v0, v116, 2, s50
	ds_read_b32 v0, v0
	v_lshl_add_u64 v[114:115], v[114:115], 0, v[142:143]
	s_waitcnt lgkmcnt(0)
	v_pk_mul_f32 v[106:107], v[106:107], v[0:1] op_sel_hi:[1,0]
	v_pk_mul_f32 v[112:113], v[112:113], v[0:1] op_sel_hi:[1,0]
	v_pk_mul_f32 v[110:111], v[110:111], v[0:1] op_sel_hi:[1,0]
	v_pk_mul_f32 v[108:109], v[108:109], v[0:1] op_sel_hi:[1,0]
	v_max_f32_e32 v106, 0, v106
	v_max_f32_e32 v107, 0, v107
	v_max_f32_e32 v110, 0, v110
	v_max_f32_e32 v111, 0, v111
	v_pk_mul_f32 v[116:117], v[106:107], v[106:107]
	v_max_f32_e32 v106, 0, v112
	v_max_f32_e32 v108, 0, v108
	v_max_f32_e32 v107, 0, v113
	v_max_f32_e32 v109, 0, v109
	v_pk_mul_f32 v[110:111], v[110:111], v[110:111]
	v_pk_mul_f32 v[112:113], v[106:107], v[106:107]
	v_pk_mul_f32 v[118:119], v[108:109], v[108:109]
	v_pk_mul_f32 v[98:99], v[98:99], v[0:1] op_sel_hi:[1,0]
	v_cvt_pk_bf16_f32 v106, v110, v111
	v_cvt_pk_bf16_f32 v107, v112, v113
	v_cvt_pk_bf16_f32 v108, v116, v117
	v_cvt_pk_bf16_f32 v109, v118, v119
	v_pk_mul_f32 v[104:105], v[104:105], v[0:1] op_sel_hi:[1,0]
	v_pk_mul_f32 v[102:103], v[102:103], v[0:1] op_sel_hi:[1,0]
	v_pk_mul_f32 v[100:101], v[100:101], v[0:1] op_sel_hi:[1,0]
	v_max_f32_e32 v98, 0, v98
	v_max_f32_e32 v99, 0, v99
	global_store_dwordx4 v[114:115], v[106:109], off
	v_max_f32_e32 v102, 0, v102
	v_max_f32_e32 v103, 0, v103
	v_pk_mul_f32 v[106:107], v[98:99], v[98:99]
	v_max_f32_e32 v98, 0, v104
	v_max_f32_e32 v100, 0, v100
	v_max_f32_e32 v99, 0, v105
	v_max_f32_e32 v101, 0, v101
	v_pk_mul_f32 v[102:103], v[102:103], v[102:103]
	v_pk_mul_f32 v[104:105], v[98:99], v[98:99]
	v_pk_mul_f32 v[108:109], v[100:101], v[100:101]
	v_cvt_pk_bf16_f32 v98, v102, v103
	v_cvt_pk_bf16_f32 v99, v104, v105
	v_cvt_pk_bf16_f32 v100, v106, v107
	v_cvt_pk_bf16_f32 v101, v108, v109
	v_add_u32_e32 v0, 32, v148
	global_store_dwordx4 v[114:115], v[98:101], off offset:64
	s_nop 1
	v_and_b32_e32 v100, 0xff, v0
	v_lshlrev_b32_e32 v0, 13, v100
	v_lshl_add_u64 v[98:99], s[54:55], 0, v[0:1]
	v_lshl_add_u32 v0, v100, 2, s50
	ds_read_b32 v0, v0
	v_lshl_add_u64 v[98:99], v[98:99], 0, v[142:143]
	s_waitcnt lgkmcnt(0)
	v_pk_mul_f32 v[90:91], v[90:91], v[0:1] op_sel_hi:[1,0]
	v_pk_mul_f32 v[96:97], v[96:97], v[0:1] op_sel_hi:[1,0]
	v_pk_mul_f32 v[94:95], v[94:95], v[0:1] op_sel_hi:[1,0]
	v_pk_mul_f32 v[92:93], v[92:93], v[0:1] op_sel_hi:[1,0]
	v_max_f32_e32 v90, 0, v90
	v_max_f32_e32 v91, 0, v91
	v_max_f32_e32 v94, 0, v94
	v_max_f32_e32 v95, 0, v95
	v_pk_mul_f32 v[100:101], v[90:91], v[90:91]
	v_max_f32_e32 v90, 0, v96
	v_max_f32_e32 v92, 0, v92
	v_max_f32_e32 v91, 0, v97
	v_max_f32_e32 v93, 0, v93
	v_pk_mul_f32 v[94:95], v[94:95], v[94:95]
	v_pk_mul_f32 v[96:97], v[90:91], v[90:91]
	v_pk_mul_f32 v[102:103], v[92:93], v[92:93]
	v_pk_mul_f32 v[82:83], v[82:83], v[0:1] op_sel_hi:[1,0]
	v_cvt_pk_bf16_f32 v90, v94, v95
	v_cvt_pk_bf16_f32 v91, v96, v97
	v_cvt_pk_bf16_f32 v92, v100, v101
	v_cvt_pk_bf16_f32 v93, v102, v103
	v_pk_mul_f32 v[88:89], v[88:89], v[0:1] op_sel_hi:[1,0]
	v_pk_mul_f32 v[86:87], v[86:87], v[0:1] op_sel_hi:[1,0]
	v_pk_mul_f32 v[84:85], v[84:85], v[0:1] op_sel_hi:[1,0]
	v_max_f32_e32 v82, 0, v82
	v_max_f32_e32 v83, 0, v83
	global_store_dwordx4 v[98:99], v[90:93], off
	v_max_f32_e32 v86, 0, v86
	v_max_f32_e32 v87, 0, v87
	v_pk_mul_f32 v[90:91], v[82:83], v[82:83]
	v_max_f32_e32 v82, 0, v88
	v_max_f32_e32 v84, 0, v84
	v_max_f32_e32 v83, 0, v89
	v_max_f32_e32 v85, 0, v85
	v_pk_mul_f32 v[86:87], v[86:87], v[86:87]
	v_pk_mul_f32 v[88:89], v[82:83], v[82:83]
	v_pk_mul_f32 v[92:93], v[84:85], v[84:85]
	v_cvt_pk_bf16_f32 v82, v86, v87
	v_cvt_pk_bf16_f32 v83, v88, v89
	v_cvt_pk_bf16_f32 v84, v90, v91
	v_cvt_pk_bf16_f32 v85, v92, v93
	v_add_u32_e32 v0, 48, v148
	global_store_dwordx4 v[98:99], v[82:85], off offset:64
	s_nop 1
	v_and_b32_e32 v84, 0xff, v0
	v_lshlrev_b32_e32 v0, 13, v84
	v_lshl_add_u64 v[82:83], s[54:55], 0, v[0:1]
	v_lshl_add_u32 v0, v84, 2, s50
	ds_read_b32 v0, v0
	v_lshl_add_u64 v[82:83], v[82:83], 0, v[142:143]
	s_waitcnt lgkmcnt(0)
	v_pk_mul_f32 v[74:75], v[74:75], v[0:1] op_sel_hi:[1,0]
	v_pk_mul_f32 v[80:81], v[80:81], v[0:1] op_sel_hi:[1,0]
	v_pk_mul_f32 v[78:79], v[78:79], v[0:1] op_sel_hi:[1,0]
	v_pk_mul_f32 v[76:77], v[76:77], v[0:1] op_sel_hi:[1,0]
	v_max_f32_e32 v74, 0, v74
	v_max_f32_e32 v75, 0, v75
	v_max_f32_e32 v78, 0, v78
	v_max_f32_e32 v79, 0, v79
	v_pk_mul_f32 v[84:85], v[74:75], v[74:75]
	v_max_f32_e32 v74, 0, v80
	v_max_f32_e32 v76, 0, v76
	v_max_f32_e32 v75, 0, v81
	v_max_f32_e32 v77, 0, v77
	v_pk_mul_f32 v[78:79], v[78:79], v[78:79]
	v_pk_mul_f32 v[80:81], v[74:75], v[74:75]
	v_pk_mul_f32 v[86:87], v[76:77], v[76:77]
	v_pk_mul_f32 v[66:67], v[66:67], v[0:1] op_sel_hi:[1,0]
	v_cvt_pk_bf16_f32 v74, v78, v79
	v_cvt_pk_bf16_f32 v75, v80, v81
	v_cvt_pk_bf16_f32 v76, v84, v85
	v_cvt_pk_bf16_f32 v77, v86, v87
	v_pk_mul_f32 v[72:73], v[72:73], v[0:1] op_sel_hi:[1,0]
	v_pk_mul_f32 v[70:71], v[70:71], v[0:1] op_sel_hi:[1,0]
	v_pk_mul_f32 v[68:69], v[68:69], v[0:1] op_sel_hi:[1,0]
	v_max_f32_e32 v66, 0, v66
	v_max_f32_e32 v67, 0, v67
	global_store_dwordx4 v[82:83], v[74:77], off
	v_max_f32_e32 v70, 0, v70
	v_max_f32_e32 v71, 0, v71
	v_pk_mul_f32 v[74:75], v[66:67], v[66:67]
	v_max_f32_e32 v66, 0, v72
	v_max_f32_e32 v68, 0, v68
	v_max_f32_e32 v67, 0, v73
	v_max_f32_e32 v69, 0, v69
	v_pk_mul_f32 v[70:71], v[70:71], v[70:71]
	v_pk_mul_f32 v[72:73], v[66:67], v[66:67]
	v_pk_mul_f32 v[76:77], v[68:69], v[68:69]
	v_cvt_pk_bf16_f32 v66, v70, v71
	v_cvt_pk_bf16_f32 v67, v72, v73
	v_cvt_pk_bf16_f32 v68, v74, v75
	v_cvt_pk_bf16_f32 v69, v76, v77
	global_store_dwordx4 v[82:83], v[66:69], off offset:64
	s_nop 1
	v_bitop3_b32 v68, v148, s51, v195 bitop3:0x6c
	v_lshlrev_b32_e32 v0, 13, v68
	v_lshl_add_u64 v[66:67], s[54:55], 0, v[0:1]
	v_lshl_add_u32 v0, v68, 2, s50
	ds_read_b32 v0, v0
	v_lshl_add_u64 v[66:67], v[66:67], 0, v[142:143]
	s_waitcnt lgkmcnt(0)
	v_pk_mul_f32 v[58:59], v[58:59], v[0:1] op_sel_hi:[1,0]
	v_pk_mul_f32 v[64:65], v[64:65], v[0:1] op_sel_hi:[1,0]
	v_pk_mul_f32 v[62:63], v[62:63], v[0:1] op_sel_hi:[1,0]
	v_pk_mul_f32 v[60:61], v[60:61], v[0:1] op_sel_hi:[1,0]
	v_max_f32_e32 v58, 0, v58
	v_max_f32_e32 v59, 0, v59
	v_max_f32_e32 v62, 0, v62
	v_max_f32_e32 v63, 0, v63
	v_pk_mul_f32 v[68:69], v[58:59], v[58:59]
	v_max_f32_e32 v58, 0, v64
	v_max_f32_e32 v60, 0, v60
	v_max_f32_e32 v59, 0, v65
	v_max_f32_e32 v61, 0, v61
	v_pk_mul_f32 v[62:63], v[62:63], v[62:63]
	v_pk_mul_f32 v[64:65], v[58:59], v[58:59]
	v_pk_mul_f32 v[70:71], v[60:61], v[60:61]
	v_pk_mul_f32 v[50:51], v[50:51], v[0:1] op_sel_hi:[1,0]
	v_cvt_pk_bf16_f32 v58, v62, v63
	v_cvt_pk_bf16_f32 v59, v64, v65
	v_cvt_pk_bf16_f32 v60, v68, v69
	v_cvt_pk_bf16_f32 v61, v70, v71
	v_pk_mul_f32 v[56:57], v[56:57], v[0:1] op_sel_hi:[1,0]
	v_pk_mul_f32 v[54:55], v[54:55], v[0:1] op_sel_hi:[1,0]
	v_pk_mul_f32 v[52:53], v[52:53], v[0:1] op_sel_hi:[1,0]
	v_max_f32_e32 v50, 0, v50
	v_max_f32_e32 v51, 0, v51
	global_store_dwordx4 v[66:67], v[58:61], off
	v_max_f32_e32 v54, 0, v54
	v_max_f32_e32 v55, 0, v55
	v_pk_mul_f32 v[58:59], v[50:51], v[50:51]
	v_max_f32_e32 v50, 0, v56
	v_max_f32_e32 v52, 0, v52
	v_max_f32_e32 v51, 0, v57
	v_max_f32_e32 v53, 0, v53
	v_pk_mul_f32 v[54:55], v[54:55], v[54:55]
	v_pk_mul_f32 v[56:57], v[50:51], v[50:51]
	v_pk_mul_f32 v[60:61], v[52:53], v[52:53]
	v_cvt_pk_bf16_f32 v50, v54, v55
	v_cvt_pk_bf16_f32 v51, v56, v57
	v_cvt_pk_bf16_f32 v52, v58, v59
	v_cvt_pk_bf16_f32 v53, v60, v61
	v_add_u32_e32 v0, 0x90, v148
	global_store_dwordx4 v[66:67], v[50:53], off offset:64
	s_nop 1
	v_and_b32_e32 v52, 0xff, v0
	v_lshlrev_b32_e32 v0, 13, v52
	v_lshl_add_u64 v[50:51], s[54:55], 0, v[0:1]
	v_lshl_add_u32 v0, v52, 2, s50
	ds_read_b32 v0, v0
	v_lshl_add_u64 v[50:51], v[50:51], 0, v[142:143]
	s_waitcnt lgkmcnt(0)
	v_pk_mul_f32 v[42:43], v[42:43], v[0:1] op_sel_hi:[1,0]
	v_pk_mul_f32 v[48:49], v[48:49], v[0:1] op_sel_hi:[1,0]
	v_pk_mul_f32 v[46:47], v[46:47], v[0:1] op_sel_hi:[1,0]
	v_pk_mul_f32 v[44:45], v[44:45], v[0:1] op_sel_hi:[1,0]
	v_max_f32_e32 v42, 0, v42
	v_max_f32_e32 v43, 0, v43
	v_max_f32_e32 v46, 0, v46
	v_max_f32_e32 v47, 0, v47
	v_pk_mul_f32 v[52:53], v[42:43], v[42:43]
	v_max_f32_e32 v42, 0, v48
	v_max_f32_e32 v44, 0, v44
	v_max_f32_e32 v43, 0, v49
	v_max_f32_e32 v45, 0, v45
	v_pk_mul_f32 v[46:47], v[46:47], v[46:47]
	v_pk_mul_f32 v[48:49], v[42:43], v[42:43]
	v_pk_mul_f32 v[54:55], v[44:45], v[44:45]
	v_pk_mul_f32 v[34:35], v[34:35], v[0:1] op_sel_hi:[1,0]
	v_cvt_pk_bf16_f32 v42, v46, v47
	v_cvt_pk_bf16_f32 v43, v48, v49
	v_cvt_pk_bf16_f32 v44, v52, v53
	v_cvt_pk_bf16_f32 v45, v54, v55
	v_pk_mul_f32 v[40:41], v[40:41], v[0:1] op_sel_hi:[1,0]
	v_pk_mul_f32 v[38:39], v[38:39], v[0:1] op_sel_hi:[1,0]
	v_pk_mul_f32 v[36:37], v[36:37], v[0:1] op_sel_hi:[1,0]
	v_max_f32_e32 v34, 0, v34
	v_max_f32_e32 v35, 0, v35
	global_store_dwordx4 v[50:51], v[42:45], off
	v_max_f32_e32 v38, 0, v38
	v_max_f32_e32 v39, 0, v39
	v_pk_mul_f32 v[42:43], v[34:35], v[34:35]
	v_max_f32_e32 v34, 0, v40
	v_max_f32_e32 v36, 0, v36
	v_max_f32_e32 v35, 0, v41
	v_max_f32_e32 v37, 0, v37
	v_pk_mul_f32 v[38:39], v[38:39], v[38:39]
	v_pk_mul_f32 v[40:41], v[34:35], v[34:35]
	v_pk_mul_f32 v[44:45], v[36:37], v[36:37]
	v_cvt_pk_bf16_f32 v34, v38, v39
	v_cvt_pk_bf16_f32 v35, v40, v41
	v_cvt_pk_bf16_f32 v36, v42, v43
	v_cvt_pk_bf16_f32 v37, v44, v45
	v_add_u32_e32 v0, 0xa0, v148
	global_store_dwordx4 v[50:51], v[34:37], off offset:64
	s_nop 1
	v_and_b32_e32 v36, 0xff, v0
	v_lshlrev_b32_e32 v0, 13, v36
	v_lshl_add_u64 v[34:35], s[54:55], 0, v[0:1]
	v_lshl_add_u32 v0, v36, 2, s50
	ds_read_b32 v0, v0
	v_lshl_add_u64 v[34:35], v[34:35], 0, v[142:143]
	s_waitcnt lgkmcnt(0)
	v_pk_mul_f32 v[26:27], v[26:27], v[0:1] op_sel_hi:[1,0]
	v_pk_mul_f32 v[32:33], v[32:33], v[0:1] op_sel_hi:[1,0]
	v_pk_mul_f32 v[30:31], v[30:31], v[0:1] op_sel_hi:[1,0]
	v_pk_mul_f32 v[28:29], v[28:29], v[0:1] op_sel_hi:[1,0]
	v_max_f32_e32 v26, 0, v26
	v_max_f32_e32 v27, 0, v27
	v_max_f32_e32 v30, 0, v30
	v_max_f32_e32 v31, 0, v31
	v_pk_mul_f32 v[36:37], v[26:27], v[26:27]
	v_max_f32_e32 v26, 0, v32
	v_max_f32_e32 v28, 0, v28
	v_max_f32_e32 v27, 0, v33
	v_max_f32_e32 v29, 0, v29
	v_pk_mul_f32 v[30:31], v[30:31], v[30:31]
	v_pk_mul_f32 v[32:33], v[26:27], v[26:27]
	v_pk_mul_f32 v[38:39], v[28:29], v[28:29]
	v_pk_mul_f32 v[18:19], v[18:19], v[0:1] op_sel_hi:[1,0]
	v_cvt_pk_bf16_f32 v26, v30, v31
	v_cvt_pk_bf16_f32 v27, v32, v33
	v_cvt_pk_bf16_f32 v28, v36, v37
	v_cvt_pk_bf16_f32 v29, v38, v39
	v_pk_mul_f32 v[24:25], v[24:25], v[0:1] op_sel_hi:[1,0]
	v_pk_mul_f32 v[22:23], v[22:23], v[0:1] op_sel_hi:[1,0]
	v_pk_mul_f32 v[20:21], v[20:21], v[0:1] op_sel_hi:[1,0]
	v_max_f32_e32 v18, 0, v18
	v_max_f32_e32 v19, 0, v19
	global_store_dwordx4 v[34:35], v[26:29], off
	v_max_f32_e32 v22, 0, v22
	v_max_f32_e32 v23, 0, v23
	v_pk_mul_f32 v[26:27], v[18:19], v[18:19]
	v_max_f32_e32 v18, 0, v24
	v_max_f32_e32 v20, 0, v20
	v_max_f32_e32 v19, 0, v25
	v_max_f32_e32 v21, 0, v21
	v_pk_mul_f32 v[22:23], v[22:23], v[22:23]
	v_pk_mul_f32 v[24:25], v[18:19], v[18:19]
	v_pk_mul_f32 v[28:29], v[20:21], v[20:21]
	v_cvt_pk_bf16_f32 v18, v22, v23
	v_cvt_pk_bf16_f32 v19, v24, v25
	v_cvt_pk_bf16_f32 v20, v26, v27
	v_cvt_pk_bf16_f32 v21, v28, v29
	v_add_u32_e32 v0, 0xb0, v148
	global_store_dwordx4 v[34:35], v[18:21], off offset:64
	s_nop 1
	v_and_b32_e32 v20, 0xff, v0
	v_lshlrev_b32_e32 v0, 13, v20
	v_lshl_add_u64 v[18:19], s[54:55], 0, v[0:1]
	v_lshl_add_u32 v0, v20, 2, s50
	ds_read_b32 v0, v0
	v_lshl_add_u64 v[18:19], v[18:19], 0, v[142:143]
	s_mov_b64 s[50:51], -1
	s_waitcnt lgkmcnt(0)
	v_pk_mul_f32 v[10:11], v[10:11], v[0:1] op_sel_hi:[1,0]
	v_pk_mul_f32 v[16:17], v[16:17], v[0:1] op_sel_hi:[1,0]
	v_pk_mul_f32 v[14:15], v[14:15], v[0:1] op_sel_hi:[1,0]
	v_pk_mul_f32 v[12:13], v[12:13], v[0:1] op_sel_hi:[1,0]
	v_max_f32_e32 v10, 0, v10
	v_max_f32_e32 v11, 0, v11
	v_max_f32_e32 v14, 0, v14
	v_max_f32_e32 v15, 0, v15
	v_pk_mul_f32 v[20:21], v[10:11], v[10:11]
	v_max_f32_e32 v10, 0, v16
	v_max_f32_e32 v12, 0, v12
	v_max_f32_e32 v11, 0, v17
	v_max_f32_e32 v13, 0, v13
	v_pk_mul_f32 v[14:15], v[14:15], v[14:15]
	v_pk_mul_f32 v[16:17], v[10:11], v[10:11]
	v_pk_mul_f32 v[22:23], v[12:13], v[12:13]
	v_pk_mul_f32 v[2:3], v[2:3], v[0:1] op_sel_hi:[1,0]
	v_cvt_pk_bf16_f32 v10, v14, v15
	v_cvt_pk_bf16_f32 v11, v16, v17
	v_cvt_pk_bf16_f32 v12, v20, v21
	v_cvt_pk_bf16_f32 v13, v22, v23
	v_pk_mul_f32 v[8:9], v[8:9], v[0:1] op_sel_hi:[1,0]
	v_pk_mul_f32 v[6:7], v[6:7], v[0:1] op_sel_hi:[1,0]
	v_pk_mul_f32 v[4:5], v[4:5], v[0:1] op_sel_hi:[1,0]
	v_max_f32_e32 v2, 0, v2
	v_max_f32_e32 v3, 0, v3
	global_store_dwordx4 v[18:19], v[10:13], off
	v_max_f32_e32 v6, 0, v6
	v_max_f32_e32 v7, 0, v7
	v_pk_mul_f32 v[10:11], v[2:3], v[2:3]
	v_max_f32_e32 v2, 0, v8
	v_max_f32_e32 v4, 0, v4
	v_max_f32_e32 v3, 0, v9
	v_max_f32_e32 v5, 0, v5
	v_pk_mul_f32 v[6:7], v[6:7], v[6:7]
	v_pk_mul_f32 v[8:9], v[2:3], v[2:3]
	v_pk_mul_f32 v[12:13], v[4:5], v[4:5]
	v_cvt_pk_bf16_f32 v2, v6, v7
	v_cvt_pk_bf16_f32 v3, v8, v9
	v_cvt_pk_bf16_f32 v4, v10, v11
	v_cvt_pk_bf16_f32 v5, v12, v13
	global_store_dwordx4 v[18:19], v[2:5], off offset:64
	s_cbranch_vccnz .LBB0_206
	s_andn2_b64 vcc, exec, s[40:41]
	s_cbranch_vccnz .LBB0_205
	s_barrier
	s_branch .LBB0_205
